# mode0: QK-phase exps moved before first LDS wait
# baseline (speedup 1.0000x reference)
; #define SBAR() __builtin_amdgcn_sched_barrier(0)
; #define SLOAD(i, k0) do { sr_[i].vs0 = *reinterpret_cast<const bf16x8*>(&Vh[(size_t)((k0) + sr) * LDQK + sc]); sr_[i].vs1 = *reinterpret_cast<const bf16x8*>(&Vh[(size_t)((k0) + 32 + sr) * LDQK + sc]); \
;     sr_[i].ks0 = *reinterpret_cast<const bf16x8*>(&Kh[(size_t)((k0) + sr) * LDQK + sc]); sr_[i].ks1 = *reinterpret_cast<const bf16x8*>(&Kh[(size_t)((k0) + 32 + sr) * LDQK + sc]); } while (0)
; #define PSM(P0, P1, MN, AL, J) partialSM<MODE>(P0, P1, m_reg, MN, AL, relq + 64 * (J), relwmin + 64 * (J), relwmax + 64 * (J), lut)
; __device__ __forceinline__ void finishSM(f32x16& p0, f32x16& p1, float alpha, float& l_reg, bf16x8& pa0, bf16x8& pa1, bf16x8& pa2, bf16x8& pa3) {
; #pragma unroll
;   for (int r = 0; r < 16; ++r) p1[r] = __builtin_amdgcn_exp2f(p1[r]);
;   float ps = 0;
; #pragma unroll
;   for (int r = 0; r < 16; ++r) ps += p0[r];
; #pragma unroll
;   for (int r = 0; r < 16; ++r) ps += p1[r];
;   { auto rr = __builtin_amdgcn_permlane32_swap(__float_as_uint(ps), __float_as_uint(ps), false, false);
;     ps = __uint_as_float(rr[0]) + __uint_as_float(rr[1]); }
;   l_reg = l_reg * alpha + ps;
;     ...
;   PK4(p0, 0, pa0); PK4(p0, 8, pa1); PK4(p1, 0, pa2); PK4(p1, 8, pa3);
;     ...
; }
; template <int ND0, int DOFF>
; __device__ __forceinline__ void qkt(f32x16& p0, f32x16& p1, const char* Ks, const bf16x8* qr, int r32, int hi) {
;   p0 = f32x16{}; p1 = f32x16{};
; #pragma unroll
;   for (int d0 = 0; d0 < ND0; ++d0) { const int cb = ((d0 + DOFF) * 16 + hi * 8) * 2;
;     bf16x8 b0 = *reinterpret_cast<const bf16x8*>(Ks + KSWZ(r32, cb));
;     bf16x8 b1 = *reinterpret_cast<const bf16x8*>(Ks + KSWZ(32 + r32, cb));
;     p0 = __builtin_amdgcn_mfma_f32_32x32x16_bf16(b0, qr[d0], p0, 0, 0, 0);
;     p1 = __builtin_amdgcn_mfma_f32_32x32x16_bf16(b1, qr[d0], p1, 0, 0, 0); }
; }
; template <int MODE>
; __device__ __forceinline__ void attn_body(const bf16_t* __restrict__ Qb, const bf16_t* __restrict__ Kh, const bf16_t* __restrict__ Vh, int NT, int krel0,
;                                           char* lds, const float* __restrict__ lutg, const AttnEpi& E) {
;     ...
;     __syncthreads();
;     SBAR(); qkt<ND0, DOFF>(pB0, pB1, K_lds + oq, qr, r32, hi);
;     finishSM(pA0, pA1, alA, l_reg, pa0, pa1, pa2, pa3); SBAR();
;     SLOAD(SO, (j + 2) * 64); SBAR();
;     pv_d0(o, vb0 + op, pa0, pa1, pa2, pa3); PSM(pB0, pB1, mnB, alB, j);
.LBB0_79:
	s_mov_b32 s69, s0
	s_waitcnt lgkmcnt(0)
	s_barrier
	s_add_i32 s0, s71, 0
	v_add_u32_e32 v70, s0, v214
	ds_read_b128 v[66:69], v70 offset:49152
	ds_read_b128 v[70:73], v70 offset:57344
	v_add_u32_e32 v162, s0, v218
	ds_read_b128 v[230:233], v162 offset:49152
	ds_read_b128 v[234:237], v162 offset:57344
	v_add_u32_e32 v162, s0, v219
	v_exp_f32_e32 v160, v160
	v_exp_f32_e32 v161, v161
	v_exp_f32_e32 v158, v158
	v_exp_f32_e32 v159, v159
	v_exp_f32_e32 v156, v156
	v_exp_f32_e32 v157, v157
	v_exp_f32_e32 v154, v154
	v_exp_f32_e32 v155, v155
	v_exp_f32_e32 v152, v152
	v_exp_f32_e32 v153, v153
	v_exp_f32_e32 v150, v150
	v_exp_f32_e32 v151, v151
	v_exp_f32_e32 v148, v148
	v_exp_f32_e32 v149, v149
	v_exp_f32_e32 v146, v146
	v_exp_f32_e32 v147, v147
	v_cvt_pk_bf16_f32 v163, v175, v177
	v_cvt_pk_bf16_f32 v229, v172, v174
	s_waitcnt lgkmcnt(3)
	v_mfma_f32_32x32x16_bf16 v[82:97], v[66:69], v[114:117], 0
	s_waitcnt lgkmcnt(2)
	v_mfma_f32_32x32x16_bf16 v[66:81], v[70:73], v[114:117], 0
	s_waitcnt lgkmcnt(1)
	v_mfma_f32_32x32x16_bf16 v[82:97], v[230:233], v[126:129], v[82:97]
	s_waitcnt lgkmcnt(0)
	v_mfma_f32_32x32x16_bf16 v[66:81], v[234:237], v[126:129], v[66:81]
	ds_read_b128 v[230:233], v162 offset:49152
	ds_read_b128 v[234:237], v162 offset:57344
	v_add_u32_e32 v162, s0, v216
	s_waitcnt lgkmcnt(1)
	v_mfma_f32_32x32x16_bf16 v[82:97], v[230:233], v[118:121], v[82:97]
	s_waitcnt lgkmcnt(0)
	v_mfma_f32_32x32x16_bf16 v[66:81], v[234:237], v[118:121], v[66:81]
	ds_read_b128 v[230:233], v162 offset:49152
	ds_read_b128 v[234:237], v162 offset:57344
	v_add_u32_e32 v162, s0, v217
	s_waitcnt lgkmcnt(1)
	v_mfma_f32_32x32x16_bf16 v[82:97], v[230:233], v[122:125], v[82:97]
	s_waitcnt lgkmcnt(0)
	v_mfma_f32_32x32x16_bf16 v[66:81], v[234:237], v[122:125], v[66:81]
	ds_read_b128 v[230:233], v162 offset:49152
	ds_read_b128 v[234:237], v162 offset:57344
	v_add_u32_e32 v162, s0, v215
	s_waitcnt lgkmcnt(1)
	v_mfma_f32_32x32x16_bf16 v[82:97], v[230:233], v[110:113], v[82:97]
	s_waitcnt lgkmcnt(0)
	v_mfma_f32_32x32x16_bf16 v[66:81], v[234:237], v[110:113], v[66:81]
	ds_read_b128 v[230:233], v162 offset:49152
	ds_read_b128 v[234:237], v162 offset:57344
	v_add_u32_e32 v162, s0, v220
	s_waitcnt lgkmcnt(1)
	v_mfma_f32_32x32x16_bf16 v[82:97], v[230:233], v[106:109], v[82:97]
	s_waitcnt lgkmcnt(0)
	v_mfma_f32_32x32x16_bf16 v[66:81], v[234:237], v[106:109], v[66:81]
	ds_read_b128 v[230:233], v162 offset:49152
	ds_read_b128 v[234:237], v162 offset:57344
	v_add_u32_e32 v162, s0, v221
	s_waitcnt lgkmcnt(1)
	v_mfma_f32_32x32x16_bf16 v[82:97], v[230:233], v[102:105], v[82:97]
	s_waitcnt lgkmcnt(0)
	v_mfma_f32_32x32x16_bf16 v[66:81], v[234:237], v[102:105], v[66:81]
	ds_read_b128 v[230:233], v162 offset:49152
	ds_read_b128 v[234:237], v162 offset:57344
	v_add_f32_e32 v162, v165, v164
	v_add_f32_e32 v162, v175, v162
	v_add_f32_e32 v162, v177, v162
	v_add_f32_e32 v162, v227, v162
	v_add_f32_e32 v162, v228, v162
	v_add_f32_e32 v162, v176, v162
	v_add_f32_e32 v162, v226, v162
	v_add_f32_e32 v162, v167, v162
	v_add_f32_e32 v162, v169, v162
	v_add_f32_e32 v162, v171, v162
	v_add_f32_e32 v162, v173, v162
	v_add_f32_e32 v162, v168, v162
	v_add_f32_e32 v162, v170, v162
	v_add_f32_e32 v162, v172, v162
	v_add_f32_e32 v162, v174, v162
	v_add_f32_e32 v162, v160, v162
	v_add_f32_e32 v162, v161, v162
	v_add_f32_e32 v162, v158, v162
	v_add_f32_e32 v162, v159, v162
	v_add_f32_e32 v162, v156, v162
	v_add_f32_e32 v162, v157, v162
	v_add_f32_e32 v162, v154, v162
	v_add_f32_e32 v162, v155, v162
	v_add_f32_e32 v162, v152, v162
	v_add_f32_e32 v162, v153, v162
	s_waitcnt lgkmcnt(1)
	v_mfma_f32_32x32x16_bf16 v[82:97], v[230:233], v[98:101], v[82:97]
	v_add_f32_e32 v162, v150, v162
	v_add_f32_e32 v162, v151, v162
	v_add_f32_e32 v162, v148, v162
	v_add_f32_e32 v162, v149, v162
	v_add_f32_e32 v162, v146, v162
	v_add_f32_e32 v223, v147, v162
	v_mov_b32_e32 v224, v223
	s_waitcnt lgkmcnt(0)
	v_mfma_f32_32x32x16_bf16 v[66:81], v[234:237], v[98:101], v[66:81]
	v_cvt_pk_bf16_f32 v162, v164, v165
	v_cvt_pk_bf16_f32 v164, v227, v228
	v_permlane32_swap_b32_e32 v223, v224
	v_cvt_pk_bf16_f32 v165, v176, v226
	v_permlane32_swap_b32_e32 v162, v164
	v_cvt_pk_bf16_f32 v226, v167, v169
	v_cvt_pk_bf16_f32 v227, v171, v173
	v_cvt_pk_bf16_f32 v228, v168, v170
	v_cvt_pk_bf16_f32 v168, v160, v161
	v_cvt_pk_bf16_f32 v169, v158, v159
	v_cvt_pk_bf16_f32 v170, v156, v157
	v_cvt_pk_bf16_f32 v171, v154, v155
	v_cvt_pk_bf16_f32 v172, v152, v153
	v_cvt_pk_bf16_f32 v173, v150, v151
	v_cvt_pk_bf16_f32 v174, v148, v149
	v_cvt_pk_bf16_f32 v175, v146, v147
	v_permlane32_swap_b32_e32 v163, v165
	v_permlane32_swap_b32_e32 v226, v228
	v_permlane32_swap_b32_e32 v227, v229
	v_permlane32_swap_b32_e32 v168, v170
	v_permlane32_swap_b32_e32 v169, v171
	v_permlane32_swap_b32_e32 v172, v174
	v_permlane32_swap_b32_e32 v173, v175
	v_add_co_u32_e32 v150, vcc, s4, v190
	s_nop 1
	v_addc_co_u32_e32 v151, vcc, -1, v191, vcc
	v_add_co_u32_e32 v154, vcc, s5, v190
	s_nop 1
	v_addc_co_u32_e32 v155, vcc, -1, v191, vcc
	global_load_dwordx4 v[146:149], v[150:151], off
	s_nop 0
	global_load_dwordx4 v[150:153], v[150:151], off offset:-512
	s_nop 0
	global_load_dwordx4 v[158:161], v[154:155], off
	s_nop 0
	global_load_dwordx4 v[154:157], v[154:155], off offset:-512
	v_add_u32_e32 v208, s68, v209
	ds_read_b64_tr_b16 v[230:231], v208 offset:0
	ds_read_b64_tr_b16 v[232:233], v208 offset:0x800
	ds_read_b64_tr_b16 v[234:235], v208 offset:0x1000
	ds_read_b64_tr_b16 v[236:237], v208 offset:0x1800
	ds_read_b64_tr_b16 v[238:239], v208 offset:0x2000
	ds_read_b64_tr_b16 v[240:241], v208 offset:0x2800
	ds_read_b64_tr_b16 v[242:243], v208 offset:0x3000
	ds_read_b64_tr_b16 v[244:245], v208 offset:0x3800
	s_waitcnt lgkmcnt(0)
; #define SBAR() __builtin_amdgcn_sched_barrier(0)
; template <int D0> __device__ __forceinline__ void pv_one(f32x16& od, int vb, bf16x8 pa0, bf16x8 pa1, bf16x8 pa2, bf16x8 pa3) {
;   const s16x4 l0 = tr_read<v_rd_off(D0, 0, 0)>(vb), h0 = tr_read<v_rd_off(D0, 0, 1)>(vb), l1 = tr_read<v_rd_off(D0, 1, 0)>(vb), h1 = tr_read<v_rd_off(D0, 1, 1)>(vb);
;   const s16x4 l2 = tr_read<v_rd_off(D0, 2, 0)>(vb), h2 = tr_read<v_rd_off(D0, 2, 1)>(vb), l3 = tr_read<v_rd_off(D0, 3, 0)>(vb), h3 = tr_read<v_rd_off(D0, 3, 1)>(vb);
;   asm volatile("s_waitcnt lgkmcnt(0)" ::: "memory"); SBAR();
;     ...
;   od = __builtin_amdgcn_mfma_f32_32x32x16_bf16(pa0, PK(l0, h0), od, 0, 0, 0);
;   od = __builtin_amdgcn_mfma_f32_32x32x16_bf16(pa1, PK(l1, h1), od, 0, 0, 0);
;   od = __builtin_amdgcn_mfma_f32_32x32x16_bf16(pa2, PK(l2, h2), od, 0, 0, 0);
;   od = __builtin_amdgcn_mfma_f32_32x32x16_bf16(pa3, PK(l3, h3), od, 0, 0, 0);
;     ...
; }
; __device__ __forceinline__ void pv_d0(f32x16* o, int vb, bf16x8 pa0, bf16x8 pa1, bf16x8 pa2, bf16x8 pa3) {
;   pv_one<0>(o[0], vb, pa0, pa1, pa2, pa3); pv_one<1>(o[1], vb, pa0, pa1, pa2, pa3); pv_one<2>(o[2], vb, pa0, pa1, pa2, pa3); pv_one<3>(o[3], vb, pa0, pa1, pa2, pa3);
	s_nop 0
	v_mfma_f32_32x32x16_bf16 v[18:33], v[162:165], v[230:233], v[18:33]
	ds_read_b64_tr_b16 v[230:231], v208 offset:0x200
	ds_read_b64_tr_b16 v[232:233], v208 offset:0xa00
	v_mfma_f32_32x32x16_bf16 v[18:33], v[226:229], v[234:237], v[18:33]
	ds_read_b64_tr_b16 v[234:235], v208 offset:0x1200
	ds_read_b64_tr_b16 v[236:237], v208 offset:0x1a00
	v_mfma_f32_32x32x16_bf16 v[18:33], v[168:171], v[238:241], v[18:33]
	ds_read_b64_tr_b16 v[238:239], v208 offset:0x2200
	ds_read_b64_tr_b16 v[240:241], v208 offset:0x2a00
	v_mfma_f32_32x32x16_bf16 v[18:33], v[172:175], v[242:245], v[18:33]
	ds_read_b64_tr_b16 v[242:243], v208 offset:0x3200
	ds_read_b64_tr_b16 v[244:245], v208 offset:0x3a00
	s_waitcnt lgkmcnt(0)
	v_mfma_f32_32x32x16_bf16 v[50:65], v[162:165], v[230:233], v[50:65]
	ds_read_b64_tr_b16 v[230:231], v208 offset:0x400
	ds_read_b64_tr_b16 v[232:233], v208 offset:0xc00
	v_mfma_f32_32x32x16_bf16 v[50:65], v[226:229], v[234:237], v[50:65]
	ds_read_b64_tr_b16 v[234:235], v208 offset:0x1400
	ds_read_b64_tr_b16 v[236:237], v208 offset:0x1c00
	v_mfma_f32_32x32x16_bf16 v[50:65], v[168:171], v[238:241], v[50:65]
	ds_read_b64_tr_b16 v[238:239], v208 offset:0x2400
	ds_read_b64_tr_b16 v[240:241], v208 offset:0x2c00
	v_mfma_f32_32x32x16_bf16 v[50:65], v[172:175], v[242:245], v[50:65]
	ds_read_b64_tr_b16 v[242:243], v208 offset:0x3400
	ds_read_b64_tr_b16 v[244:245], v208 offset:0x3c00
	s_waitcnt lgkmcnt(0)
	v_mfma_f32_32x32x16_bf16 v[34:49], v[162:165], v[230:233], v[34:49]
	ds_read_b64_tr_b16 v[230:231], v208 offset:0x600
	ds_read_b64_tr_b16 v[232:233], v208 offset:0xe00
	v_mfma_f32_32x32x16_bf16 v[34:49], v[226:229], v[234:237], v[34:49]
	ds_read_b64_tr_b16 v[234:235], v208 offset:0x1600
	ds_read_b64_tr_b16 v[236:237], v208 offset:0x1e00
	v_mfma_f32_32x32x16_bf16 v[34:49], v[168:171], v[238:241], v[34:49]
	ds_read_b64_tr_b16 v[238:239], v208 offset:0x2600
	ds_read_b64_tr_b16 v[240:241], v208 offset:0x2e00
	v_mfma_f32_32x32x16_bf16 v[34:49], v[172:175], v[242:245], v[34:49]
	ds_read_b64_tr_b16 v[242:243], v208 offset:0x3600
	ds_read_b64_tr_b16 v[244:245], v208 offset:0x3e00
	s_waitcnt lgkmcnt(0)
	v_mfma_f32_32x32x16_bf16 v[2:17], v[162:165], v[230:233], v[2:17]
	v_mfma_f32_32x32x16_bf16 v[2:17], v[226:229], v[234:237], v[2:17]
	v_mfma_f32_32x32x16_bf16 v[2:17], v[168:171], v[238:241], v[2:17]
	v_mfma_f32_32x32x16_bf16 v[2:17], v[172:175], v[242:245], v[2:17]
	s_add_i32 s72, s69, 0
	v_add_u32_e32 v163, s72, v210
	s_waitcnt vmcnt(4)
	s_waitcnt vmcnt(4)
	ds_write_b128 v163, v[130:133]
	v_add_u32_e32 v163, s72, v211
	ds_write_b128 v163, v[138:141]
	v_add_u32_e32 v163, s72, v212
	ds_write_b128 v163, v[142:145] offset:49152
	v_add_u32_e32 v163, s72, v213
	ds_write_b128 v163, v[134:137] offset:49152
; template <int MODE>
; __device__ __forceinline__ void partialSM(f32x16& p0, f32x16& p1, float& m_reg, float& mn, float& alpha, int relh, int relw_min, int relw_max, const float* lut) {
;     ...
;     const float mnC = -mn * C;
; #pragma unroll
;     for (int r = 0; r < 16; ++r) p0[r] = fmaf(p0[r], C, mnC);
; #pragma unroll
;     for (int r = 0; r < 16; ++r) p1[r] = fmaf(p1[r], C, mnC);
; #pragma unroll
;     for (int r = 0; r < 16; ++r) p0[r] = __builtin_amdgcn_exp2f(p0[r]);
; __device__ __forceinline__ void finishSM(f32x16& p0, f32x16& p1, float alpha, float& l_reg, bf16x8& pa0, bf16x8& pa1, bf16x8& pa2, bf16x8& pa3) {
; #pragma unroll
;   for (int r = 0; r < 16; ++r) p1[r] = __builtin_amdgcn_exp2f(p1[r]);
;   float ps = 0;
; #pragma unroll
;   for (int r = 0; r < 16; ++r) ps += p0[r];
; #pragma unroll
;   for (int r = 0; r < 16; ++r) ps += p1[r];
;   { auto rr = __builtin_amdgcn_permlane32_swap(__float_as_uint(ps), __float_as_uint(ps), false, false);
;     ps = __uint_as_float(rr[0]) + __uint_as_float(rr[1]); }
;   l_reg = l_reg * alpha + ps;
;     ...
;   PK4(p0, 0, pa0); PK4(p0, 8, pa1); PK4(p1, 0, pa2); PK4(p1, 8, pa3);
;     ...
; }
; template <int ND0, int DOFF>
; __device__ __forceinline__ void qkt(f32x16& p0, f32x16& p1, const char* Ks, const bf16x8* qr, int r32, int hi) {
;   p0 = f32x16{}; p1 = f32x16{};
; #pragma unroll
;   for (int d0 = 0; d0 < ND0; ++d0) { const int cb = ((d0 + DOFF) * 16 + hi * 8) * 2;
;     bf16x8 b0 = *reinterpret_cast<const bf16x8*>(Ks + KSWZ(r32, cb));
;     bf16x8 b1 = *reinterpret_cast<const bf16x8*>(Ks + KSWZ(32 + r32, cb));
;     p0 = __builtin_amdgcn_mfma_f32_32x32x16_bf16(b0, qr[d0], p0, 0, 0, 0);
;     p1 = __builtin_amdgcn_mfma_f32_32x32x16_bf16(b1, qr[d0], p1, 0, 0, 0); }
; }
.LBB0_83:
	v_mov_b32_e32 v226, v166
	v_mul_f32_e32 v170, 0xbe0293ee, v226
	v_fmamk_f32 v82, v82, 0x3e0293ee, v170
	v_fmamk_f32 v83, v83, 0x3e0293ee, v170
	v_fmamk_f32 v84, v84, 0x3e0293ee, v170
	v_fmamk_f32 v85, v85, 0x3e0293ee, v170
	v_fmamk_f32 v86, v86, 0x3e0293ee, v170
	v_fmamk_f32 v87, v87, 0x3e0293ee, v170
	v_fmamk_f32 v88, v88, 0x3e0293ee, v170
	v_fmamk_f32 v89, v89, 0x3e0293ee, v170
	v_fmamk_f32 v90, v90, 0x3e0293ee, v170
	v_fmamk_f32 v91, v91, 0x3e0293ee, v170
	v_fmamk_f32 v92, v92, 0x3e0293ee, v170
	v_fmamk_f32 v93, v93, 0x3e0293ee, v170
	v_fmamk_f32 v94, v94, 0x3e0293ee, v170
	v_fmamk_f32 v95, v95, 0x3e0293ee, v170
	v_fmamk_f32 v96, v96, 0x3e0293ee, v170
	v_fmamk_f32 v97, v97, 0x3e0293ee, v170
	v_fmamk_f32 v171, v66, 0x3e0293ee, v170
	v_fmamk_f32 v172, v67, 0x3e0293ee, v170
	v_fmamk_f32 v173, v68, 0x3e0293ee, v170
	v_fmamk_f32 v174, v69, 0x3e0293ee, v170
	v_fmamk_f32 v175, v70, 0x3e0293ee, v170
	v_fmamk_f32 v176, v71, 0x3e0293ee, v170
	v_fmamk_f32 v177, v72, 0x3e0293ee, v170
	v_fmamk_f32 v227, v73, 0x3e0293ee, v170
	v_fmamk_f32 v228, v74, 0x3e0293ee, v170
	v_fmamk_f32 v229, v75, 0x3e0293ee, v170
	v_fmamk_f32 v230, v76, 0x3e0293ee, v170
	v_fmamk_f32 v231, v77, 0x3e0293ee, v170
	v_fmamk_f32 v232, v78, 0x3e0293ee, v170
	v_fmamk_f32 v233, v79, 0x3e0293ee, v170
	v_fmamk_f32 v234, v80, 0x3e0293ee, v170
	v_fmac_f32_e32 v170, 0x3e0293ee, v81
	v_exp_f32_e32 v235, v82
	v_exp_f32_e32 v236, v83
	v_exp_f32_e32 v237, v84
	v_exp_f32_e32 v238, v85
	v_exp_f32_e32 v239, v86
	v_exp_f32_e32 v240, v87
	v_exp_f32_e32 v241, v88
	v_exp_f32_e32 v242, v89
	v_exp_f32_e32 v243, v90
	v_exp_f32_e32 v244, v91
	v_exp_f32_e32 v245, v92
	v_exp_f32_e32 v246, v93
	v_exp_f32_e32 v247, v94
	v_exp_f32_e32 v248, v95
	v_exp_f32_e32 v249, v96
	v_exp_f32_e32 v250, v97
	s_waitcnt lgkmcnt(0)
	s_barrier
	v_add_u32_e32 v70, s72, v214
	ds_read_b128 v[66:69], v70 offset:49152
	ds_read_b128 v[70:73], v70 offset:57344
	v_add_u32_e32 v166, s72, v218
	ds_read_b128 v[162:165], v166 offset:49152
	ds_read_b128 v[166:169], v166 offset:57344
	v_exp_f32_e32 v171, v171
	v_exp_f32_e32 v172, v172
	v_exp_f32_e32 v173, v173
	v_exp_f32_e32 v174, v174
	v_exp_f32_e32 v175, v175
	v_exp_f32_e32 v176, v176
	v_exp_f32_e32 v177, v177
	v_exp_f32_e32 v227, v227
	v_exp_f32_e32 v228, v228
	v_exp_f32_e32 v251, v229
	v_exp_f32_e32 v195, v230
	v_exp_f32_e32 v231, v231
	v_exp_f32_e32 v232, v232
	v_exp_f32_e32 v233, v233
	v_exp_f32_e32 v234, v234
	v_exp_f32_e32 v194, v170
	v_cvt_pk_bf16_f32 v170, v171, v172
	s_waitcnt lgkmcnt(3)
	v_mfma_f32_32x32x16_bf16 v[82:97], v[66:69], v[114:117], 0
	s_waitcnt lgkmcnt(2)
	v_mfma_f32_32x32x16_bf16 v[66:81], v[70:73], v[114:117], 0
	s_waitcnt lgkmcnt(1)
	v_mfma_f32_32x32x16_bf16 v[82:97], v[162:165], v[126:129], v[82:97]
	s_waitcnt lgkmcnt(0)
	v_mfma_f32_32x32x16_bf16 v[66:81], v[166:169], v[126:129], v[66:81]
	v_add_u32_e32 v166, s72, v219
	ds_read_b128 v[162:165], v166 offset:49152
	ds_read_b128 v[166:169], v166 offset:57344
	s_waitcnt lgkmcnt(1)
	v_mfma_f32_32x32x16_bf16 v[82:97], v[162:165], v[118:121], v[82:97]
	s_waitcnt lgkmcnt(0)
	v_mfma_f32_32x32x16_bf16 v[66:81], v[166:169], v[118:121], v[66:81]
	v_add_u32_e32 v166, s72, v216
	ds_read_b128 v[162:165], v166 offset:49152
	ds_read_b128 v[166:169], v166 offset:57344
	s_waitcnt lgkmcnt(1)
	v_mfma_f32_32x32x16_bf16 v[82:97], v[162:165], v[122:125], v[82:97]
	s_waitcnt lgkmcnt(0)
	v_mfma_f32_32x32x16_bf16 v[66:81], v[166:169], v[122:125], v[66:81]
	v_add_u32_e32 v166, s72, v217
	ds_read_b128 v[162:165], v166 offset:49152
	ds_read_b128 v[166:169], v166 offset:57344
	s_waitcnt lgkmcnt(1)
	v_mfma_f32_32x32x16_bf16 v[82:97], v[162:165], v[110:113], v[82:97]
	s_waitcnt lgkmcnt(0)
	v_mfma_f32_32x32x16_bf16 v[66:81], v[166:169], v[110:113], v[66:81]
	v_add_u32_e32 v166, s72, v215
	ds_read_b128 v[162:165], v166 offset:49152
	ds_read_b128 v[166:169], v166 offset:57344
	s_waitcnt lgkmcnt(1)
	v_mfma_f32_32x32x16_bf16 v[82:97], v[162:165], v[106:109], v[82:97]
	s_waitcnt lgkmcnt(0)
	v_mfma_f32_32x32x16_bf16 v[66:81], v[166:169], v[106:109], v[66:81]
	v_add_u32_e32 v166, s72, v220
	ds_read_b128 v[162:165], v166 offset:49152
	ds_read_b128 v[166:169], v166 offset:57344
	s_waitcnt lgkmcnt(1)
	v_mfma_f32_32x32x16_bf16 v[82:97], v[162:165], v[102:105], v[82:97]
	s_waitcnt lgkmcnt(0)
	v_mfma_f32_32x32x16_bf16 v[66:81], v[166:169], v[102:105], v[66:81]
	v_add_u32_e32 v166, s72, v221
	ds_read_b128 v[162:165], v166 offset:49152
	ds_read_b128 v[166:169], v166 offset:57344
	s_waitcnt lgkmcnt(1)
	v_mfma_f32_32x32x16_bf16 v[82:97], v[162:165], v[98:101], v[82:97]
	v_add_f32_e32 v162, v236, v235
	v_add_f32_e32 v162, v237, v162
	v_add_f32_e32 v162, v238, v162
	v_add_f32_e32 v162, v239, v162
	v_add_f32_e32 v162, v240, v162
	v_add_f32_e32 v162, v241, v162
	v_add_f32_e32 v162, v242, v162
	v_add_f32_e32 v162, v243, v162
	v_add_f32_e32 v162, v244, v162
	v_add_f32_e32 v162, v245, v162
	v_add_f32_e32 v162, v246, v162
	v_add_f32_e32 v162, v247, v162
	v_add_f32_e32 v162, v248, v162
	v_add_f32_e32 v162, v249, v162
	v_add_f32_e32 v162, v250, v162
	v_add_f32_e32 v162, v171, v162
	v_add_f32_e32 v162, v172, v162
	v_add_f32_e32 v162, v173, v162
	v_add_f32_e32 v162, v174, v162
	v_add_f32_e32 v162, v175, v162
	v_add_f32_e32 v162, v176, v162
	v_add_f32_e32 v162, v177, v162
	v_add_f32_e32 v162, v227, v162
	v_add_f32_e32 v162, v228, v162
	v_add_f32_e32 v162, v251, v162
	s_waitcnt lgkmcnt(0)
	v_mfma_f32_32x32x16_bf16 v[66:81], v[166:169], v[98:101], v[66:81]
	v_add_f32_e32 v162, v195, v162
	v_add_f32_e32 v162, v231, v162
	v_add_f32_e32 v162, v232, v162
	v_add_f32_e32 v162, v233, v162
	v_add_f32_e32 v162, v234, v162
	v_add_f32_e32 v229, v194, v162
	v_mov_b32_e32 v230, v229
	v_cvt_pk_bf16_f32 v162, v235, v236
	v_cvt_pk_bf16_f32 v163, v237, v238
	v_cvt_pk_bf16_f32 v164, v239, v240
	v_cvt_pk_bf16_f32 v165, v241, v242
	v_cvt_pk_bf16_f32 v166, v243, v244
	v_cvt_pk_bf16_f32 v167, v245, v246
	v_cvt_pk_bf16_f32 v168, v247, v248
	v_cvt_pk_bf16_f32 v169, v249, v250
	v_cvt_pk_bf16_f32 v171, v173, v174
	v_cvt_pk_bf16_f32 v172, v175, v176
	v_cvt_pk_bf16_f32 v173, v177, v227
	v_cvt_pk_bf16_f32 v174, v228, v251
	v_cvt_pk_bf16_f32 v175, v195, v231
	v_cvt_pk_bf16_f32 v176, v232, v233
	v_cvt_pk_bf16_f32 v177, v234, v194
	v_permlane32_swap_b32_e32 v229, v230
	v_permlane32_swap_b32_e32 v162, v164
	v_permlane32_swap_b32_e32 v163, v165
	v_permlane32_swap_b32_e32 v166, v168
	v_permlane32_swap_b32_e32 v167, v169
	v_permlane32_swap_b32_e32 v170, v172
	v_permlane32_swap_b32_e32 v171, v173
	v_permlane32_swap_b32_e32 v174, v176
	v_permlane32_swap_b32_e32 v175, v177
	s_cmp_ge_u32 s66, s11
	s_cbranch_scc1 .LBB0_85
	v_add_co_u32_e32 v134, vcc, 0xfffb8000, v190
	s_nop 1
	v_addc_co_u32_e32 v135, vcc, -1, v191, vcc
	global_load_dwordx4 v[130:133], v[134:135], off
	global_load_dwordx4 v[142:145], v[134:135], off offset:-512
	global_load_dwordx4 v[138:141], v[190:191], off
	s_nop 0
	global_load_dwordx4 v[134:137], v[190:191], off offset:-512
